# v39: v38 + final f32 y stores write-through (sc1): less dirty L2 for the end-of-kernel write-back
# baseline (speedup 1.0000x reference)
; __device__ __forceinline__ v4u pack8(const float (&f)[8]) { v4u w; w.x = pg8::cvt_pk_bf16(f[0], f[1]); w.y = pg8::cvt_pk_bf16(f[2], f[3]); w.z = pg8::cvt_pk_bf16(f[4], f[5]); w.w = pg8::cvt_pk_bf16(f[6], f[7]); return w; }
; __device__ __forceinline__ void ew_finish(const EwRow& r, const float (&gg)[2][8], float* __restrict__ Xrow32, bf16* __restrict__ Xrow16, bool dst16, float* __restrict__ rsp, bool write_xn, int lane) {
;     ...
;     if (dst16) { v4u* Xr = (v4u*)Xrow16 + lane;
; #pragma unroll
;         for (int j = 0; j < 2; ++j) Xr[64 * j] = pack8(x[j]); }
;     else { f32x4* Xr = (f32x4*)Xrow32 + 2 * lane;
; #pragma unroll
;         for (int j = 0; j < 2; ++j) { Xr[128 * j] = (f32x4){x[j][0], x[j][1], x[j][2], x[j][3]}; Xr[128 * j + 1] = (f32x4){x[j][4], x[j][5], x[j][6], x[j][7]}; } }
.LBB0_441:
	global_store_dwordx4 v68, v[48:51], s[12:13] sc1
	global_store_dwordx4 v68, v[52:55], s[12:13] offset:16 sc1
	global_store_dwordx4 v68, v[56:59], s[12:13] offset:2048 sc1
	global_store_dwordx4 v68, v[60:63], s[12:13] offset:2064 sc1
	s_cbranch_execnz .LBB0_440
